# LN phases +8/+9: LayerNorm gain/bias vectors loaded once per wave in the loop preheader instead of seven dependent flat-load round trips per row
# speedup vs baseline: 1.0103x; 1.0049x over previous
.LBB0_1229:
	s_andn2_b64 vcc, exec, s[0:1]
	s_cbranch_vccnz .LBB0_1408
	v_readlane_b32 s10, v243, 26
	v_readlane_b32 s11, v243, 27
	s_mov_b64 s[0:1], -1
	s_and_b64 vcc, exec, s[10:11]
	s_cbranch_vccz .LBB0_1345
	v_readlane_b32 s0, v239, 48
	v_mov_b32_e32 v2, v0
	v_readlane_b32 s18, v243, 28
	v_mov_b32_e32 v3, s0
	ds_read2_b64 v[4:7], v3 offset1:1
	v_readlane_b32 s0, v238, 14
	v_readlane_b32 s1, v238, 15
	s_cmp_lg_u32 s0, 3
	v_readlane_b32 s19, v243, 29
	s_cselect_b64 s[10:11], -1, 0
	s_waitcnt lgkmcnt(0)
	v_readfirstlane_b32 s0, v5
	v_readfirstlane_b32 s1, v4
	v_readfirstlane_b32 s14, v7
	s_andn2_b64 vcc, exec, s[18:19]
	v_readfirstlane_b32 s15, v6
	s_cbranch_vccnz .LBB0_1250
	v_and_b32_e32 v4, 63, v2
	v_and_b32_e32 v2, 64, v203
	v_add_u32_e32 v2, 64, v2
	v_xor_b32_e32 v3, 1, v203
	v_cmp_lt_i32_e32 vcc, v3, v2
	v_readlane_b32 s18, v238, 14
	v_readlane_b32 s19, v238, 15
	v_cndmask_b32_e32 v3, v203, v3, vcc
	v_lshlrev_b32_e32 v60, 2, v3
	v_xor_b32_e32 v3, 2, v203
	v_cmp_lt_i32_e32 vcc, v3, v2
	s_lshl_b32 s90, s18, 11
	s_lshl_b64 s[18:19], s[90:91], 2
	v_cndmask_b32_e32 v3, v203, v3, vcc
	v_lshlrev_b32_e32 v61, 2, v3
	v_xor_b32_e32 v3, 4, v203
	v_cmp_lt_i32_e32 vcc, v3, v2
	s_add_u32 s20, s15, s18
	s_addc_u32 s21, s14, s19
	v_cndmask_b32_e32 v3, v203, v3, vcc
	v_lshlrev_b32_e32 v62, 2, v3
	v_xor_b32_e32 v3, 8, v203
	v_cmp_lt_i32_e32 vcc, v3, v2
	s_add_u32 s14, s1, s18
	v_lshlrev_b32_e32 v172, 5, v4
	v_cndmask_b32_e32 v3, v203, v3, vcc
	v_lshlrev_b32_e32 v63, 2, v3
	v_xor_b32_e32 v3, 16, v203
	v_cmp_lt_i32_e32 vcc, v3, v2
	s_addc_u32 s15, s0, s19
	v_readlane_b32 s0, v240, 21
	v_cndmask_b32_e32 v3, v203, v3, vcc
	v_lshlrev_b32_e32 v64, 2, v3
	v_xor_b32_e32 v3, 32, v203
	v_cmp_lt_i32_e32 vcc, v3, v2
	v_readlane_b32 s1, v240, 22
	v_lshl_add_u64 v[10:11], s[14:15], 0, v[172:173]
	v_cndmask_b32_e32 v2, v203, v3, vcc
	v_lshlrev_b32_e32 v65, 2, v2
	v_or_b32_e32 v2, 0x1000, v172
	v_mov_b32_e32 v3, v173
	v_lshl_add_u64 v[14:15], s[14:15], 0, v[2:3]
	v_lshl_add_u64 v[16:17], s[20:21], 0, v[2:3]
	v_or_b32_e32 v2, 0x1800, v172
	v_lshl_add_u64 v[18:19], s[14:15], 0, v[2:3]
	v_lshl_add_u64 v[20:21], s[20:21], 0, v[2:3]
	v_lshlrev_b32_e32 v2, 4, v4
	v_lshl_add_u64 v[22:23], s[0:1], 0, v[2:3]
	v_readlane_b32 s0, v240, 27
	v_readlane_b32 s1, v240, 28
	v_lshl_add_u64 v[12:13], s[20:21], 0, v[172:173]
	s_nop 0
	v_lshl_add_u64 v[24:25], s[0:1], 0, v[172:173]
	v_readlane_b32 s0, v240, 25
	s_mov_b32 s14, s0
	v_readlane_b32 s1, v240, 26
	global_load_dwordx4 v[112:115], v[10:11], off
	global_load_dwordx4 v[116:119], v[12:13], off
	global_load_dwordx4 v[120:123], v[10:11], off offset:16
	global_load_dwordx4 v[124:127], v[12:13], off offset:16
	global_load_dwordx4 v[128:131], v[10:11], off offset:2048
	global_load_dwordx4 v[132:135], v[12:13], off offset:2048
	global_load_dwordx4 v[136:139], v[10:11], off offset:2064
	global_load_dwordx4 v[140:143], v[12:13], off offset:2064
	global_load_dwordx4 v[144:147], v[14:15], off
	global_load_dwordx4 v[148:151], v[16:17], off
	global_load_dwordx4 v[152:155], v[14:15], off offset:16
	global_load_dwordx4 v[156:159], v[16:17], off offset:16
	global_load_dwordx4 v[160:163], v[20:21], off
	global_load_dwordx4 v[164:167], v[18:19], off
	global_load_dwordx4 v[204:207], v[18:19], off offset:16
	global_load_dwordx4 v[208:211], v[20:21], off offset:16
	s_branch .LBB0_1234

.LBB0_1234:
	global_load_dwordx4 v[2:5], v[22:23], off
	global_load_dwordx4 v[6:9], v[22:23], off offset:1024
	global_load_dwordx4 v[46:49], v[22:23], off offset:2048
	global_load_dwordx4 v[28:31], v[22:23], off offset:3072
	s_waitcnt vmcnt(0)
	v_and_b32_e32 v59, 0xffff0000, v2
	v_lshlrev_b32_e32 v50, 16, v8
	v_and_b32_e32 v51, 0xffff0000, v8
	v_lshlrev_b32_e32 v52, 16, v9
	v_and_b32_e32 v53, 0xffff0000, v9
	v_lshlrev_b32_e32 v9, 16, v2
	v_lshlrev_b32_e32 v8, 16, v4
	v_and_b32_e32 v58, 0xffff0000, v4
	v_lshlrev_b32_e32 v67, 16, v3
	v_lshlrev_b32_e32 v66, 16, v5
	v_and_b32_e32 v69, 0xffff0000, v3
	v_and_b32_e32 v68, 0xffff0000, v5
	v_pk_add_f32 v[2:3], v[8:9], v[58:59]
	v_pk_add_f32 v[4:5], v[66:67], v[68:69]
	v_lshlrev_b32_e32 v55, 16, v7
	v_pk_add_f32 v[2:3], v[2:3], v[4:5]
	v_lshlrev_b32_e32 v54, 16, v6
	v_add_f32_e32 v3, 0, v3
	v_and_b32_e32 v57, 0xffff0000, v7
	v_and_b32_e32 v56, 0xffff0000, v6
	v_add_f32_e32 v43, v2, v3
	v_pk_add_f32 v[2:3], v[54:55], v[56:57]
	v_lshlrev_b32_e32 v38, 16, v46
	v_pk_add_f32 v[2:3], v[2:3], v[2:3] op_sel_hi:[0,1]
	v_and_b32_e32 v44, 0xffff0000, v46
	v_lshlrev_b32_e32 v40, 16, v47
	v_and_b32_e32 v42, 0xffff0000, v47
	v_add_f32_e32 v39, v50, v51
	v_add_f32_e32 v45, v52, v53
	v_mov_b32_e32 v41, v3
	v_pk_add_f32 v[4:5], v[38:39], v[44:45]
	v_pk_add_f32 v[2:3], v[40:41], v[42:43]
	v_lshlrev_b32_e32 v47, 16, v49
	v_lshlrev_b32_e32 v46, 16, v48
	v_and_b32_e32 v49, 0xffff0000, v49
	v_and_b32_e32 v48, 0xffff0000, v48
	v_pk_add_f32 v[2:3], v[4:5], v[2:3]
	v_pk_add_f32 v[4:5], v[46:47], v[48:49]
	v_lshlrev_b32_e32 v32, 16, v28
	v_and_b32_e32 v33, 0xffff0000, v28
	v_lshlrev_b32_e32 v26, 16, v29
	v_and_b32_e32 v27, 0xffff0000, v29
	v_pk_add_f32 v[2:3], v[2:3], v[2:3] op_sel_hi:[0,1]
	v_pk_add_f32 v[4:5], v[4:5], v[4:5] op_sel_hi:[0,1]
	v_lshlrev_b32_e32 v28, 16, v30
	v_and_b32_e32 v36, 0xffff0000, v30
	v_lshlrev_b32_e32 v30, 16, v31
	v_and_b32_e32 v34, 0xffff0000, v31
	v_add_f32_e32 v29, v32, v33
	v_add_f32_e32 v37, v26, v27
	v_mov_b32_e32 v31, v5
	v_mov_b32_e32 v35, v3
	v_pk_add_f32 v[6:7], v[28:29], v[36:37]
	v_pk_add_f32 v[2:3], v[30:31], v[34:35]
	s_nop 0
	v_pk_add_f32 v[2:3], v[6:7], v[2:3]
	s_nop 0
	v_add_f32_e32 v2, v2, v3
	s_waitcnt lgkmcnt(0)
	s_nop 1
	v_add_f32_dpp v2, v2, v2 quad_perm:[1,0,3,2] row_mask:0xf bank_mask:0xf
	s_nop 1
	v_add_f32_dpp v2, v2, v2 quad_perm:[2,3,0,1] row_mask:0xf bank_mask:0xf
	s_nop 1
	v_add_f32_dpp v2, v2, v2 row_half_mirror row_mask:0xf bank_mask:0xf
	s_nop 1
	v_add_f32_dpp v2, v2, v2 row_mirror row_mask:0xf bank_mask:0xf
	s_nop 1
	v_add_f32_dpp v2, v2, v2 row_bcast:15 row_mask:0xa bank_mask:0xf
	s_nop 1
	v_add_f32_dpp v2, v2, v2 row_bcast:31 row_mask:0xc bank_mask:0xf
	s_nop 1
	v_readlane_b32 s100, v2, 63
	v_mov_b32_e32 v29, s100
	v_fmac_f32_e32 v59, 0xba000000, v29
	v_fmac_f32_e32 v9, 0xba000000, v29
	v_fmac_f32_e32 v58, 0xba000000, v29
	v_fmac_f32_e32 v8, 0xba000000, v29
	v_mov_b32_e32 v6, v8
	v_mov_b32_e32 v2, v9
	v_mov_b32_e32 v4, v9
	v_mov_b32_e32 v5, v8
	v_mov_b32_e32 v8, v59
	v_mov_b32_e32 v9, v58
	v_fmac_f32_e32 v69, 0xba000000, v29
	v_fmac_f32_e32 v67, 0xba000000, v29
	v_fmac_f32_e32 v68, 0xba000000, v29
	v_fmac_f32_e32 v66, 0xba000000, v29
	v_pk_mul_f32 v[8:9], v[8:9], v[8:9]
	v_mov_b32_e32 v7, v58
	v_mov_b32_e32 v3, v59
	v_pk_fma_f32 v[58:59], v[4:5], v[4:5], v[8:9]
	v_mov_b32_e32 v8, v66
	v_mov_b32_e32 v4, v67
	v_mov_b32_e32 v70, v67
	v_mov_b32_e32 v71, v66
	v_mov_b32_e32 v66, v69
	v_mov_b32_e32 v67, v68
	v_pk_mul_f32 v[66:67], v[66:67], v[66:67]
	v_fmac_f32_e32 v57, 0xba000000, v29
	v_pk_fma_f32 v[66:67], v[70:71], v[70:71], v[66:67]
	v_fmac_f32_e32 v55, 0xba000000, v29
	v_fmac_f32_e32 v56, 0xba000000, v29
	v_fmac_f32_e32 v54, 0xba000000, v29
	v_mov_b32_e32 v9, v68
	v_mov_b32_e32 v5, v69
	v_pk_add_f32 v[58:59], v[58:59], v[66:67]
	v_mov_b32_e32 v66, v55
	v_mov_b32_e32 v67, v57
	v_mov_b32_e32 v68, v54
	v_mov_b32_e32 v69, v56
	v_pk_add_f32 v[58:59], v[58:59], v[58:59] op_sel_hi:[0,1]
	v_pk_mul_f32 v[66:67], v[66:67], v[66:67]
	v_pk_mul_f32 v[68:69], v[68:69], v[68:69]
	v_fmac_f32_e32 v50, 0xba000000, v29
	v_pk_mov_b32 v[70:71], v[68:69], v[66:67] op_sel:[1,0]
	v_mov_b32_e32 v69, v67
	v_fmac_f32_e32 v52, 0xba000000, v29
	v_fmac_f32_e32 v51, 0xba000000, v29
	v_mul_f32_e32 v58, v50, v50
	v_pk_add_f32 v[66:67], v[70:71], v[68:69]
	v_fmac_f32_e32 v53, 0xba000000, v29
	v_pk_fma_f32 v[68:69], v[50:51], v[50:51], v[58:59] op_sel_hi:[1,1,0]
	v_mul_f32_e32 v58, v52, v52
	v_pk_add_f32 v[66:67], v[66:67], v[66:67] op_sel_hi:[0,1]
	v_pk_fma_f32 v[70:71], v[52:53], v[52:53], v[58:59] op_sel_hi:[1,1,0]
	v_fmac_f32_e32 v42, 0xba000000, v29
	v_fmac_f32_e32 v40, 0xba000000, v29
	v_fmac_f32_e32 v44, 0xba000000, v29
	v_fmac_f32_e32 v38, 0xba000000, v29
	v_mul_f32_e32 v68, v38, v38
	v_mul_f32_e32 v70, v44, v44
	v_mul_f32_e32 v66, v40, v40
	v_mul_f32_e32 v58, v42, v42
	v_pk_add_f32 v[68:69], v[68:69], v[70:71]
	v_pk_add_f32 v[58:59], v[66:67], v[58:59]
	v_fmac_f32_e32 v49, 0xba000000, v29
	v_fmac_f32_e32 v47, 0xba000000, v29
	v_fmac_f32_e32 v48, 0xba000000, v29
	v_fmac_f32_e32 v46, 0xba000000, v29
	v_pk_add_f32 v[58:59], v[68:69], v[58:59]
	v_mov_b32_e32 v66, v47
	v_mov_b32_e32 v67, v49
	v_mov_b32_e32 v68, v46
	v_mov_b32_e32 v69, v48
	v_pk_add_f32 v[58:59], v[58:59], v[58:59] op_sel_hi:[0,1]
	v_pk_mul_f32 v[66:67], v[66:67], v[66:67]
	v_pk_mul_f32 v[68:69], v[68:69], v[68:69]
	v_fmac_f32_e32 v32, 0xba000000, v29
	v_pk_mov_b32 v[70:71], v[68:69], v[66:67] op_sel:[1,0]
	v_mov_b32_e32 v69, v67
	v_fmac_f32_e32 v26, 0xba000000, v29
	v_fmac_f32_e32 v33, 0xba000000, v29
	v_mul_f32_e32 v58, v32, v32
	v_pk_add_f32 v[66:67], v[70:71], v[68:69]
	v_fmac_f32_e32 v27, 0xba000000, v29
	v_pk_fma_f32 v[68:69], v[32:33], v[32:33], v[58:59] op_sel_hi:[1,1,0]
	v_mul_f32_e32 v58, v26, v26
	v_pk_add_f32 v[66:67], v[66:67], v[66:67] op_sel_hi:[0,1]
	v_pk_fma_f32 v[70:71], v[26:27], v[26:27], v[58:59] op_sel_hi:[1,1,0]
	v_fmac_f32_e32 v34, 0xba000000, v29
	v_fmac_f32_e32 v30, 0xba000000, v29
	v_fmac_f32_e32 v36, 0xba000000, v29
	v_fmac_f32_e32 v28, 0xba000000, v29
	v_mul_f32_e32 v68, v28, v28
	v_mul_f32_e32 v70, v36, v36
	v_mul_f32_e32 v66, v30, v30
	v_mul_f32_e32 v58, v34, v34
	v_pk_add_f32 v[68:69], v[68:69], v[70:71]
	v_pk_add_f32 v[58:59], v[66:67], v[58:59]
	s_nop 0
	v_pk_add_f32 v[58:59], v[68:69], v[58:59]
	s_nop 0
	v_add_f32_e32 v29, v58, v59
	s_waitcnt lgkmcnt(0)
	s_nop 1
	v_add_f32_dpp v29, v29, v29 quad_perm:[1,0,3,2] row_mask:0xf bank_mask:0xf
	s_nop 1
	v_add_f32_dpp v29, v29, v29 quad_perm:[2,3,0,1] row_mask:0xf bank_mask:0xf
	s_nop 1
	v_add_f32_dpp v29, v29, v29 row_half_mirror row_mask:0xf bank_mask:0xf
	s_nop 1
	v_add_f32_dpp v29, v29, v29 row_mirror row_mask:0xf bank_mask:0xf
	s_nop 1
	v_add_f32_dpp v29, v29, v29 row_bcast:15 row_mask:0xa bank_mask:0xf
	s_nop 1
	v_add_f32_dpp v29, v29, v29 row_bcast:31 row_mask:0xc bank_mask:0xf
	s_nop 1
	v_readlane_b32 s100, v29, 63
	v_mov_b32_e32 v29, s100
	v_fmamk_f32 v29, v29, 0x3a000000, v171
	v_cmp_gt_f32_e32 vcc, s9, v29
	v_mul_f32_e32 v31, 0x4f800000, v29
	s_nop 0
	v_cndmask_b32_e32 v29, v29, v31, vcc
	v_sqrt_f32_e32 v31, v29
	s_nop 0
	v_add_u32_e32 v35, -1, v31
	v_fma_f32 v37, -v35, v31, v29
	v_cmp_ge_f32_e64 s[0:1], 0, v37
	v_add_u32_e32 v37, 1, v31
	s_nop 0
	v_cndmask_b32_e64 v35, v31, v35, s[0:1]
	v_fma_f32 v31, -v37, v31, v29
	v_cmp_lt_f32_e64 s[0:1], 0, v31
	s_nop 1
	v_cndmask_b32_e64 v31, v35, v37, s[0:1]
	v_mul_f32_e32 v35, 0x37800000, v31
	v_cndmask_b32_e32 v31, v31, v35, vcc
	v_cmp_class_f32_e32 vcc, v29, v200
	s_nop 1
	v_cndmask_b32_e32 v29, v31, v29, vcc
	v_div_scale_f32 v31, s[0:1], v29, v29, 1.0
	v_rcp_f32_e32 v35, v31
	s_mov_b64 s[0:1], -1
	v_fma_f32 v37, -v31, v35, 1.0
	v_fmac_f32_e32 v35, v37, v35
	v_div_scale_f32 v37, vcc, 1.0, v29, 1.0
	v_mul_f32_e32 v39, v37, v35
	v_fma_f32 v41, -v31, v39, v37
	v_fmac_f32_e32 v39, v41, v35
	v_fma_f32 v31, -v31, v39, v37
	v_div_fmas_f32 v31, v31, v35, v39
	v_div_fixup_f32 v58, v31, v29, 1.0
	v_pk_mul_f32 v[70:71], v[2:3], v[58:59] op_sel_hi:[1,0]
	v_pk_mul_f32 v[72:73], v[4:5], v[58:59] op_sel_hi:[1,0]
	s_nop 0
	s_nop 0
	v_pk_mul_f32 v[6:7], v[6:7], v[58:59] op_sel_hi:[1,0]
	v_pk_mul_f32 v[8:9], v[8:9], v[58:59] op_sel_hi:[1,0]
	s_and_b64 vcc, exec, s[10:11]
	s_nop 0
	v_pk_fma_f32 v[4:5], v[114:115], v[72:73], v[118:119]
	v_pk_fma_f32 v[2:3], v[112:113], v[70:71], v[116:117]
	s_nop 0
	s_nop 0
	s_nop 0
	v_pk_fma_f32 v[8:9], v[122:123], v[8:9], v[126:127]
	v_pk_fma_f32 v[6:7], v[120:121], v[6:7], v[124:125]
	s_cbranch_vccz .LBB0_1236
	v_add_co_u32_e32 v70, vcc, 0xd8900000, v22
	v_cvt_pk_bf16_f32 v66, v2, v3
	v_cvt_pk_bf16_f32 v67, v4, v5
	v_cvt_pk_bf16_f32 v68, v6, v7
	v_cvt_pk_bf16_f32 v69, v8, v9
	s_nop 1
	v_addc_co_u32_e32 v71, vcc, -1, v23, vcc
	global_store_dwordx4 v[70:71], v[66:69], off
	s_mov_b64 s[0:1], 0

.LBB0_1238:
	s_nop 0
	v_mov_b32_e32 v2, v54
	v_mov_b32_e32 v3, v56
	v_mov_b32_e32 v59, v58
	v_mov_b32_e32 v66, v58
	v_mov_b32_e32 v67, v58
	v_mov_b32_e32 v56, v55
	v_pk_mul_f32 v[54:55], v[56:57], v[66:67]
	v_pk_mul_f32 v[56:57], v[2:3], v[58:59]
	s_nop 0
	s_nop 0
	v_cndmask_b32_e64 v29, 0, 1, s[10:11]
	s_mov_b64 s[0:1], -1
	v_cmp_ne_u32_e64 s[38:39], 1, v29
	s_andn2_b64 vcc, exec, s[10:11]
	s_nop 0
	v_pk_fma_f32 v[4:5], v[54:55], v[130:131], v[134:135]
	v_pk_fma_f32 v[2:3], v[56:57], v[128:129], v[132:133]
	v_pk_mul_f32 v[54:55], v[52:53], v[66:67]
	v_pk_mul_f32 v[56:57], v[50:51], v[58:59]
	s_nop 0
	s_nop 0
	s_nop 0
	v_pk_fma_f32 v[8:9], v[54:55], v[138:139], v[142:143]
	v_pk_fma_f32 v[6:7], v[56:57], v[136:137], v[140:141]
	s_cbranch_vccnz .LBB0_1240
	v_add_co_u32_e32 v54, vcc, 0xd8901000, v22
	s_mov_b64 s[0:1], 0
	s_nop 0
	v_addc_co_u32_e32 v55, vcc, -1, v23, vcc
	v_cvt_pk_bf16_f32 v50, v2, v3
	v_cvt_pk_bf16_f32 v51, v4, v5
	v_cvt_pk_bf16_f32 v52, v6, v7
	v_cvt_pk_bf16_f32 v53, v8, v9
	global_store_dwordx4 v[54:55], v[50:53], off offset:-3072

.LBB0_1242:
	s_nop 0
	s_nop 0
	s_nop 0
	v_mov_b32_e32 v39, v44
	v_mov_b32_e32 v50, v58
	v_mov_b32_e32 v51, v58
	v_mov_b32_e32 v41, v42
	v_pk_mul_f32 v[40:41], v[40:41], v[50:51]
	v_pk_mul_f32 v[38:39], v[38:39], v[58:59]
	v_mov_b32_e32 v44, v46
	v_mov_b32_e32 v45, v48
	v_mov_b32_e32 v48, v47
	v_pk_mul_f32 v[42:43], v[48:49], v[50:51]
	v_pk_mul_f32 v[44:45], v[44:45], v[58:59]
	s_mov_b64 s[0:1], -1
	s_and_b64 vcc, exec, s[38:39]
	s_nop 0
	v_pk_fma_f32 v[4:5], v[40:41], v[146:147], v[150:151]
	v_pk_fma_f32 v[2:3], v[38:39], v[144:145], v[148:149]
	s_nop 0
	s_nop 0
	s_nop 0
	v_pk_fma_f32 v[8:9], v[42:43], v[154:155], v[158:159]
	v_pk_fma_f32 v[6:7], v[44:45], v[152:153], v[156:157]
	s_cbranch_vccnz .LBB0_1244
	v_add_co_u32_e32 v42, vcc, 0xd8901000, v22
	s_mov_b64 s[0:1], 0
	s_nop 0
	v_addc_co_u32_e32 v43, vcc, -1, v23, vcc
	v_cvt_pk_bf16_f32 v38, v2, v3
	v_cvt_pk_bf16_f32 v39, v4, v5
	v_cvt_pk_bf16_f32 v40, v6, v7
	v_cvt_pk_bf16_f32 v41, v8, v9
	global_store_dwordx4 v[42:43], v[38:41], off offset:-2048

.LBB0_1246:
	s_nop 0
	s_nop 0
	s_nop 0
	s_nop 0
	s_nop 0
	v_mov_b32_e32 v29, v36
	v_mov_b32_e32 v36, v58
	v_mov_b32_e32 v37, v58
	v_mov_b32_e32 v31, v34
	v_pk_mul_f32 v[32:33], v[32:33], v[58:59]
	v_pk_mul_f32 v[26:27], v[26:27], v[36:37]
	v_pk_mul_f32 v[30:31], v[30:31], v[36:37]
	v_pk_mul_f32 v[28:29], v[28:29], v[58:59]
	s_and_b64 vcc, exec, s[38:39]
	s_mov_b64 s[0:1], -1
	s_nop 0
	v_pk_fma_f32 v[4:5], v[26:27], v[166:167], v[162:163]
	v_pk_fma_f32 v[2:3], v[32:33], v[164:165], v[160:161]
	v_pk_fma_f32 v[8:9], v[30:31], v[206:207], v[210:211]
	v_pk_fma_f32 v[6:7], v[28:29], v[204:205], v[208:209]
	s_cbranch_vccnz .LBB0_1248
	v_add_co_u32_e32 v30, vcc, 0xd8901000, v22
	s_mov_b64 s[0:1], 0
	s_nop 0
	v_addc_co_u32_e32 v31, vcc, -1, v23, vcc
	v_cvt_pk_bf16_f32 v26, v2, v3
	v_cvt_pk_bf16_f32 v27, v4, v5
	v_cvt_pk_bf16_f32 v28, v6, v7
	v_cvt_pk_bf16_f32 v29, v8, v9
	global_store_dwordx4 v[30:31], v[26:29], off offset:-1024

.LBB0_1409:
	v_readlane_b32 s0, v239, 48
	v_mov_b32_e32 v2, v0
	v_readlane_b32 s10, v242, 13
	v_mov_b32_e32 v3, s0
	ds_read2_b64 v[4:7], v3 offset1:1
	v_readlane_b32 s11, v242, 14
	s_andn2_b64 vcc, exec, s[10:11]
	s_waitcnt lgkmcnt(0)
	v_readfirstlane_b32 s0, v5
	v_readfirstlane_b32 s1, v4
	v_readfirstlane_b32 s14, v7
	v_readfirstlane_b32 s15, v6
	s_cbranch_vccnz .LBB0_1428
	v_and_b32_e32 v4, 63, v2
	v_and_b32_e32 v2, 64, v203
	v_add_u32_e32 v2, 64, v2
	v_xor_b32_e32 v3, 1, v203
	v_cmp_lt_i32_e32 vcc, v3, v2
	v_readlane_b32 s10, v238, 14
	v_readlane_b32 s11, v238, 15
	v_cndmask_b32_e32 v3, v203, v3, vcc
	v_lshlrev_b32_e32 v60, 2, v3
	v_xor_b32_e32 v3, 2, v203
	v_cmp_lt_i32_e32 vcc, v3, v2
	s_mov_b32 s18, s10
	s_cmp_lg_u32 s10, 3
	v_cndmask_b32_e32 v3, v203, v3, vcc
	v_lshlrev_b32_e32 v61, 2, v3
	v_xor_b32_e32 v3, 4, v203
	v_cmp_lt_i32_e32 vcc, v3, v2
	s_cselect_b64 s[10:11], -1, 0
	s_lshl_b32 s90, s18, 11
	v_cndmask_b32_e32 v3, v203, v3, vcc
	v_lshlrev_b32_e32 v62, 2, v3
	v_xor_b32_e32 v3, 8, v203
	v_cmp_lt_i32_e32 vcc, v3, v2
	s_lshl_b64 s[18:19], s[90:91], 2
	s_add_u32 s20, s15, s18
	v_cndmask_b32_e32 v3, v203, v3, vcc
	v_lshlrev_b32_e32 v63, 2, v3
	v_xor_b32_e32 v3, 16, v203
	v_cmp_lt_i32_e32 vcc, v3, v2
	s_addc_u32 s21, s14, s19
	s_add_u32 s14, s1, s18
	v_cndmask_b32_e32 v3, v203, v3, vcc
	v_lshlrev_b32_e32 v64, 2, v3
	v_xor_b32_e32 v3, 32, v203
	v_cmp_lt_i32_e32 vcc, v3, v2
	v_lshlrev_b32_e32 v172, 5, v4
	s_addc_u32 s15, s0, s19
	v_cndmask_b32_e32 v2, v203, v3, vcc
	v_lshlrev_b32_e32 v65, 2, v2
	v_or_b32_e32 v2, 0x1000, v172
	v_mov_b32_e32 v3, v173
	v_lshl_add_u64 v[14:15], s[14:15], 0, v[2:3]
	v_lshl_add_u64 v[16:17], s[20:21], 0, v[2:3]
	v_or_b32_e32 v2, 0x1800, v172
	v_readlane_b32 s0, v240, 40
	v_lshl_add_u64 v[18:19], s[14:15], 0, v[2:3]
	v_lshl_add_u64 v[20:21], s[20:21], 0, v[2:3]
	v_lshlrev_b32_e32 v2, 4, v4
	v_readlane_b32 s1, v240, 41
	v_lshl_add_u64 v[10:11], s[14:15], 0, v[172:173]
	v_lshl_add_u64 v[12:13], s[20:21], 0, v[172:173]
	v_lshl_add_u64 v[22:23], s[0:1], 0, v[2:3]
	v_readlane_b32 s0, v240, 46
	v_readlane_b32 s1, v240, 47
	s_nop 1
	v_lshl_add_u64 v[24:25], s[0:1], 0, v[172:173]
	v_readlane_b32 s0, v240, 44
	s_mov_b32 s14, s0
	v_readlane_b32 s1, v240, 45
	global_load_dwordx4 v[112:115], v[10:11], off
	global_load_dwordx4 v[116:119], v[12:13], off
	global_load_dwordx4 v[120:123], v[10:11], off offset:16
	global_load_dwordx4 v[124:127], v[12:13], off offset:16
	global_load_dwordx4 v[128:131], v[10:11], off offset:2048
	global_load_dwordx4 v[132:135], v[12:13], off offset:2048
	global_load_dwordx4 v[136:139], v[10:11], off offset:2064
	global_load_dwordx4 v[140:143], v[12:13], off offset:2064
	global_load_dwordx4 v[144:147], v[14:15], off
	global_load_dwordx4 v[148:151], v[16:17], off
	global_load_dwordx4 v[152:155], v[14:15], off offset:16
	global_load_dwordx4 v[156:159], v[16:17], off offset:16
	global_load_dwordx4 v[160:163], v[20:21], off
	global_load_dwordx4 v[164:167], v[18:19], off
	global_load_dwordx4 v[204:207], v[18:19], off offset:16
	global_load_dwordx4 v[208:211], v[20:21], off offset:16
	s_branch .LBB0_1412
